# attention ping-pong loop: K operand reads issued pairwise 4 steps ahead, both score MFMAs of a step back to back
# speedup vs baseline: 1.0643x; 1.0006x over previous
; __device__ __forceinline__ void qkt(f32x16& p0, f32x16& p1, const char* Kn, const char* Kp, const bf16x8* qr, int r32, int hi) {
;   p0 = f32x16{}; p1 = f32x16{};
; #pragma unroll
;   for (int d0 = 0; d0 < 8; ++d0) { int cb = (d0 * 16 + hi * 8) * 2;
;     bf16x8 b0 = *reinterpret_cast<const bf16x8*>(Kn + KSWZ(r32, cb));
;     bf16x8 b1 = *reinterpret_cast<const bf16x8*>(Kn + KSWZ(32 + r32, cb));
;     p0 = __builtin_amdgcn_mfma_f32_32x32x16_bf16(b0, qr[d0], p0, 0, 0, 0);
;     p1 = __builtin_amdgcn_mfma_f32_32x32x16_bf16(b1, qr[d0], p1, 0, 0, 0); }
; #pragma unroll
;   for (int d1 = 0; d1 < 4; ++d1) { int cb = (d1 * 16 + hi * 8) * 2;
;     bf16x8 b0 = *reinterpret_cast<const bf16x8*>(Kp + KPSWZ(r32, cb));
;     bf16x8 b1 = *reinterpret_cast<const bf16x8*>(Kp + KPSWZ(32 + r32, cb));
;     p0 = __builtin_amdgcn_mfma_f32_32x32x16_bf16(b0, qr[8 + d1], p0, 0, 0, 0);
;     p1 = __builtin_amdgcn_mfma_f32_32x32x16_bf16(b1, qr[8 + d1], p1, 0, 0, 0); }
.Lpp_ga:
	ds_read_b128 v[192:195], v160
	ds_read_b128 v[196:199], v160 offset:8192
	ds_read_b128 v[200:203], v161
	ds_read_b128 v[204:207], v161 offset:8192
	ds_read_b128 v[208:211], v162
	ds_read_b128 v[212:215], v162 offset:8192
	ds_read_b128 v[216:219], v163
	ds_read_b128 v[220:223], v163 offset:8192
	s_waitcnt lgkmcnt(6)
	v_mfma_f32_32x32x16_bf16 v[80:95], v[192:195], v[136:139], 0
	v_mfma_f32_32x32x16_bf16 v[64:79], v[196:199], v[136:139], 0
	ds_read_b128 v[192:195], v164
	ds_read_b128 v[196:199], v164 offset:8192
	s_waitcnt lgkmcnt(6)
	v_mfma_f32_32x32x16_bf16 v[80:95], v[200:203], v[132:135], v[80:95]
	v_mfma_f32_32x32x16_bf16 v[64:79], v[204:207], v[132:135], v[64:79]
	ds_read_b128 v[200:203], v165
	ds_read_b128 v[204:207], v165 offset:8192
	s_waitcnt lgkmcnt(6)
	v_mfma_f32_32x32x16_bf16 v[80:95], v[208:211], v[128:131], v[80:95]
	v_mfma_f32_32x32x16_bf16 v[64:79], v[212:215], v[128:131], v[64:79]
	ds_read_b128 v[208:211], v166
	ds_read_b128 v[212:215], v166 offset:8192
	s_waitcnt lgkmcnt(6)
	v_mfma_f32_32x32x16_bf16 v[80:95], v[216:219], v[124:127], v[80:95]
	v_mfma_f32_32x32x16_bf16 v[64:79], v[220:223], v[124:127], v[64:79]
	ds_read_b128 v[216:219], v167
	ds_read_b128 v[220:223], v167 offset:8192
	s_waitcnt lgkmcnt(6)
	v_mfma_f32_32x32x16_bf16 v[80:95], v[192:195], v[120:123], v[80:95]
	v_mfma_f32_32x32x16_bf16 v[64:79], v[196:199], v[120:123], v[64:79]
	ds_read_b128 v[192:195], v168
	ds_read_b128 v[196:199], v168 offset:4096
	s_waitcnt lgkmcnt(6)
	v_mfma_f32_32x32x16_bf16 v[80:95], v[200:203], v[140:143], v[80:95]
	v_mfma_f32_32x32x16_bf16 v[64:79], v[204:207], v[140:143], v[64:79]
	ds_read_b128 v[200:203], v169
	ds_read_b128 v[204:207], v169 offset:4096
	s_waitcnt lgkmcnt(6)
	v_mfma_f32_32x32x16_bf16 v[80:95], v[208:211], v[116:119], v[80:95]
	v_mfma_f32_32x32x16_bf16 v[64:79], v[212:215], v[116:119], v[64:79]
	ds_read_b128 v[208:211], v170
	ds_read_b128 v[212:215], v170 offset:4096
	s_waitcnt lgkmcnt(6)
	v_mfma_f32_32x32x16_bf16 v[80:95], v[216:219], v[112:115], v[80:95]
	v_mfma_f32_32x32x16_bf16 v[64:79], v[220:223], v[112:115], v[64:79]
	ds_read_b128 v[216:219], v171
	ds_read_b128 v[220:223], v171 offset:4096
	s_waitcnt lgkmcnt(6)
	v_mfma_f32_32x32x16_bf16 v[80:95], v[192:195], v[108:111], v[80:95]
	v_mfma_f32_32x32x16_bf16 v[64:79], v[196:199], v[108:111], v[64:79]
	s_waitcnt lgkmcnt(4)
	v_mfma_f32_32x32x16_bf16 v[80:95], v[200:203], v[104:107], v[80:95]
	v_mfma_f32_32x32x16_bf16 v[64:79], v[204:207], v[104:107], v[64:79]
	s_waitcnt lgkmcnt(2)
	v_mfma_f32_32x32x16_bf16 v[80:95], v[208:211], v[100:103], v[80:95]
	v_mfma_f32_32x32x16_bf16 v[64:79], v[212:215], v[100:103], v[64:79]
	s_waitcnt lgkmcnt(0)
	v_mfma_f32_32x32x16_bf16 v[80:95], v[216:219], v[96:99], v[80:95]
	v_mfma_f32_32x32x16_bf16 v[64:79], v[220:223], v[96:99], v[64:79]
	s_barrier

; __device__ __forceinline__ void qkt(f32x16& p0, f32x16& p1, const char* Kn, const char* Kp, const bf16x8* qr, int r32, int hi) {
;   p0 = f32x16{}; p1 = f32x16{};
; #pragma unroll
;   for (int d0 = 0; d0 < 8; ++d0) { int cb = (d0 * 16 + hi * 8) * 2;
;     bf16x8 b0 = *reinterpret_cast<const bf16x8*>(Kn + KSWZ(r32, cb));
;     bf16x8 b1 = *reinterpret_cast<const bf16x8*>(Kn + KSWZ(32 + r32, cb));
;     p0 = __builtin_amdgcn_mfma_f32_32x32x16_bf16(b0, qr[d0], p0, 0, 0, 0);
;     p1 = __builtin_amdgcn_mfma_f32_32x32x16_bf16(b1, qr[d0], p1, 0, 0, 0); }
; #pragma unroll
;   for (int d1 = 0; d1 < 4; ++d1) { int cb = (d1 * 16 + hi * 8) * 2;
;     bf16x8 b0 = *reinterpret_cast<const bf16x8*>(Kp + KPSWZ(r32, cb));
;     bf16x8 b1 = *reinterpret_cast<const bf16x8*>(Kp + KPSWZ(32 + r32, cb));
;     p0 = __builtin_amdgcn_mfma_f32_32x32x16_bf16(b0, qr[8 + d1], p0, 0, 0, 0);
;     p1 = __builtin_amdgcn_mfma_f32_32x32x16_bf16(b1, qr[8 + d1], p1, 0, 0, 0); }
; }
; __device__ __forceinline__ int v_st(int k, int c) { const int kk = (k & ~0xC) | ((k & 4) << 1) | ((k & 8) >> 1); return ((kk >> 3) * 4 + (c >> 5)) * 512 + ((kk & 7) * 32 + (c & 31)) * 2; }
; __device__ __forceinline__ int v_rd_base(int lane) { return ((lane & 3) << 3) | (((lane >> 2) & 3) << 6) | (((lane >> 4) & 1) << 5) | (((lane >> 5) & 1) << 8); }
; template <int OFF> __device__ __forceinline__ s16x4 tr_read(int vb) {
;   s16x4 r; asm volatile("ds_read_b64_tr_b16 %0, %1 offset:%2" : "=&v"(r) : "v"(vb), "i"(OFF) : "memory"); return r;
; }
; template <int D0> __device__ __forceinline__ void pv_one(f32x16& od, int vb, bf16x8 pa0, bf16x8 pa1, bf16x8 pa2, bf16x8 pa3) {
;   const s16x4 l0 = tr_read<v_rd_off(D0, 0, 0)>(vb), h0 = tr_read<v_rd_off(D0, 0, 1)>(vb), l1 = tr_read<v_rd_off(D0, 1, 0)>(vb), h1 = tr_read<v_rd_off(D0, 1, 1)>(vb);
;   const s16x4 l2 = tr_read<v_rd_off(D0, 2, 0)>(vb), h2 = tr_read<v_rd_off(D0, 2, 1)>(vb), l3 = tr_read<v_rd_off(D0, 3, 0)>(vb), h3 = tr_read<v_rd_off(D0, 3, 1)>(vb);
;   asm volatile("s_waitcnt lgkmcnt(0)" ::: "memory"); SBAR();
;     ...
;   od = __builtin_amdgcn_mfma_f32_32x32x16_bf16(pa0, PK(l0, h0), od, 0, 0, 0);
;   od = __builtin_amdgcn_mfma_f32_32x32x16_bf16(pa1, PK(l1, h1), od, 0, 0, 0);
;   od = __builtin_amdgcn_mfma_f32_32x32x16_bf16(pa2, PK(l2, h2), od, 0, 0, 0);
;   od = __builtin_amdgcn_mfma_f32_32x32x16_bf16(pa3, PK(l3, h3), od, 0, 0, 0);
;     ...
; }
.Lpp_send_a:
	s_waitcnt lgkmcnt(0)
	s_barrier
	s_add_i32 s11, s11, 1
	ds_read_b128 v[192:195], v160 offset:16384
	ds_read_b128 v[196:199], v160 offset:24576
	ds_read_b128 v[200:203], v161 offset:16384
	ds_read_b128 v[204:207], v161 offset:24576
	ds_read_b128 v[208:211], v162 offset:16384
	ds_read_b128 v[212:215], v162 offset:24576
	ds_read_b128 v[216:219], v163 offset:16384
	ds_read_b128 v[220:223], v163 offset:24576
	s_waitcnt lgkmcnt(6)
	v_mfma_f32_32x32x16_bf16 v[80:95], v[192:195], v[136:139], 0
	v_mfma_f32_32x32x16_bf16 v[64:79], v[196:199], v[136:139], 0
	ds_read_b128 v[192:195], v164 offset:16384
	ds_read_b128 v[196:199], v164 offset:24576
	s_waitcnt lgkmcnt(6)
	v_mfma_f32_32x32x16_bf16 v[80:95], v[200:203], v[132:135], v[80:95]
	v_mfma_f32_32x32x16_bf16 v[64:79], v[204:207], v[132:135], v[64:79]
	ds_read_b128 v[200:203], v165 offset:16384
	ds_read_b128 v[204:207], v165 offset:24576
	s_waitcnt lgkmcnt(6)
	v_mfma_f32_32x32x16_bf16 v[80:95], v[208:211], v[128:131], v[80:95]
	v_mfma_f32_32x32x16_bf16 v[64:79], v[212:215], v[128:131], v[64:79]
	ds_read_b128 v[208:211], v166 offset:16384
	ds_read_b128 v[212:215], v166 offset:24576
	s_waitcnt lgkmcnt(6)
	v_mfma_f32_32x32x16_bf16 v[80:95], v[216:219], v[124:127], v[80:95]
	v_mfma_f32_32x32x16_bf16 v[64:79], v[220:223], v[124:127], v[64:79]
	ds_read_b128 v[216:219], v167 offset:16384
	ds_read_b128 v[220:223], v167 offset:24576
	s_waitcnt lgkmcnt(6)
	v_mfma_f32_32x32x16_bf16 v[80:95], v[192:195], v[120:123], v[80:95]
	v_mfma_f32_32x32x16_bf16 v[64:79], v[196:199], v[120:123], v[64:79]
	ds_read_b128 v[192:195], v168 offset:8192
	ds_read_b128 v[196:199], v168 offset:12288
	s_waitcnt lgkmcnt(6)
	v_mfma_f32_32x32x16_bf16 v[80:95], v[200:203], v[140:143], v[80:95]
	v_mfma_f32_32x32x16_bf16 v[64:79], v[204:207], v[140:143], v[64:79]
	ds_read_b128 v[200:203], v169 offset:8192
	ds_read_b128 v[204:207], v169 offset:12288
	s_waitcnt lgkmcnt(6)
	v_mfma_f32_32x32x16_bf16 v[80:95], v[208:211], v[116:119], v[80:95]
	v_mfma_f32_32x32x16_bf16 v[64:79], v[212:215], v[116:119], v[64:79]
	ds_read_b128 v[208:211], v170 offset:8192
	ds_read_b128 v[212:215], v170 offset:12288
	s_waitcnt lgkmcnt(6)
	v_mfma_f32_32x32x16_bf16 v[80:95], v[216:219], v[112:115], v[80:95]
	v_mfma_f32_32x32x16_bf16 v[64:79], v[220:223], v[112:115], v[64:79]
	ds_read_b128 v[216:219], v171 offset:8192
	ds_read_b128 v[220:223], v171 offset:12288
	s_waitcnt lgkmcnt(6)
	v_mfma_f32_32x32x16_bf16 v[80:95], v[192:195], v[108:111], v[80:95]
	v_mfma_f32_32x32x16_bf16 v[64:79], v[196:199], v[108:111], v[64:79]
	ds_read_b64_tr_b16 v[192:193], v174 offset:0
	ds_read_b64_tr_b16 v[194:195], v174 offset:2048
	ds_read_b64_tr_b16 v[196:197], v174 offset:4096
	ds_read_b64_tr_b16 v[198:199], v174 offset:6144
	s_waitcnt lgkmcnt(8)
	v_mfma_f32_32x32x16_bf16 v[80:95], v[200:203], v[104:107], v[80:95]
	v_mfma_f32_32x32x16_bf16 v[64:79], v[204:207], v[104:107], v[64:79]
	ds_read_b64_tr_b16 v[200:201], v174 offset:8192
	ds_read_b64_tr_b16 v[202:203], v174 offset:10240
	ds_read_b64_tr_b16 v[204:205], v174 offset:12288
	ds_read_b64_tr_b16 v[206:207], v174 offset:14336
	s_waitcnt lgkmcnt(10)
	v_mfma_f32_32x32x16_bf16 v[80:95], v[208:211], v[100:103], v[80:95]
	v_mfma_f32_32x32x16_bf16 v[64:79], v[212:215], v[100:103], v[64:79]
	ds_read_b64_tr_b16 v[208:209], v174 offset:512
	ds_read_b64_tr_b16 v[210:211], v174 offset:2560
	ds_read_b64_tr_b16 v[212:213], v174 offset:4608
	ds_read_b64_tr_b16 v[214:215], v174 offset:6656
	s_waitcnt lgkmcnt(12)
	v_mfma_f32_32x32x16_bf16 v[80:95], v[216:219], v[96:99], v[80:95]
	v_mfma_f32_32x32x16_bf16 v[64:79], v[220:223], v[96:99], v[64:79]
	ds_read_b64_tr_b16 v[216:217], v174 offset:8704
	ds_read_b64_tr_b16 v[218:219], v174 offset:10752
	ds_read_b64_tr_b16 v[220:221], v174 offset:12800
	ds_read_b64_tr_b16 v[222:223], v174 offset:14848
	s_waitcnt lgkmcnt(12)
	v_mfma_f32_32x32x16_bf16 v[0:15], v[144:147], v[192:195], v[0:15]
	ds_read_b64_tr_b16 v[192:193], v174 offset:1024
	ds_read_b64_tr_b16 v[194:195], v174 offset:3072
	v_mfma_f32_32x32x16_bf16 v[0:15], v[148:151], v[196:199], v[0:15]
	ds_read_b64_tr_b16 v[196:197], v174 offset:5120
	ds_read_b64_tr_b16 v[198:199], v174 offset:7168
	s_waitcnt lgkmcnt(12)
	v_mfma_f32_32x32x16_bf16 v[0:15], v[152:155], v[200:203], v[0:15]
	ds_read_b64_tr_b16 v[200:201], v174 offset:9216
	ds_read_b64_tr_b16 v[202:203], v174 offset:11264
	v_mfma_f32_32x32x16_bf16 v[0:15], v[156:159], v[204:207], v[0:15]
	ds_read_b64_tr_b16 v[204:205], v174 offset:13312
	ds_read_b64_tr_b16 v[206:207], v174 offset:15360
	s_waitcnt lgkmcnt(12)
	v_mfma_f32_32x32x16_bf16 v[48:63], v[144:147], v[208:211], v[48:63]
	ds_read_b64_tr_b16 v[208:209], v174 offset:1536
	ds_read_b64_tr_b16 v[210:211], v174 offset:3584
	v_mfma_f32_32x32x16_bf16 v[48:63], v[148:151], v[212:215], v[48:63]
	ds_read_b64_tr_b16 v[212:213], v174 offset:5632
	ds_read_b64_tr_b16 v[214:215], v174 offset:7680
	s_waitcnt lgkmcnt(12)
	v_mfma_f32_32x32x16_bf16 v[48:63], v[152:155], v[216:219], v[48:63]
	ds_read_b64_tr_b16 v[216:217], v174 offset:9728
	ds_read_b64_tr_b16 v[218:219], v174 offset:11776
	v_mfma_f32_32x32x16_bf16 v[48:63], v[156:159], v[220:223], v[48:63]
	ds_read_b64_tr_b16 v[220:221], v174 offset:13824
	ds_read_b64_tr_b16 v[222:223], v174 offset:15872
	s_waitcnt lgkmcnt(12)
	v_mfma_f32_32x32x16_bf16 v[32:47], v[144:147], v[192:195], v[32:47]
	v_mfma_f32_32x32x16_bf16 v[32:47], v[148:151], v[196:199], v[32:47]
	s_waitcnt lgkmcnt(8)
	v_mfma_f32_32x32x16_bf16 v[32:47], v[152:155], v[200:203], v[32:47]
	v_mfma_f32_32x32x16_bf16 v[32:47], v[156:159], v[204:207], v[32:47]
	s_waitcnt lgkmcnt(4)
	v_mfma_f32_32x32x16_bf16 v[16:31], v[144:147], v[208:211], v[16:31]
	v_mfma_f32_32x32x16_bf16 v[16:31], v[148:151], v[212:215], v[16:31]
	s_waitcnt lgkmcnt(0)
	v_mfma_f32_32x32x16_bf16 v[16:31], v[152:155], v[216:219], v[16:31]
	v_mfma_f32_32x32x16_bf16 v[16:31], v[156:159], v[220:223], v[16:31]
	s_barrier
; #define SBAR() __builtin_amdgcn_sched_barrier(0)
; #define SLOAD(j) do { const int r0_ = TROW(j); const bf16_t* a_ = KVh + (size_t)(r0_ + sr) * LDKV + sc; const bf16_t* b_ = KVh + (size_t)(r0_ + 32 + sr) * LDKV + sc; \
;     vs0 = ld8(a_ + 128); vs1 = ld8(b_ + 128); ks0 = ld8(a_); ks1 = ld8(b_); kp0 = ld8(KPh + (size_t)(r0_ + pr) * LDKP + pc); } while (0)
; __device__ __forceinline__ void partialSM(f32x16& p0, f32x16& p1, float& m_reg, float& mn, float& alpha) {
;   constexpr float C = SCALE * 1.4426950408889634f;
;   float pmax = p0[0]; for (int r = 1; r < 16; ++r) pmax = fmaxf(pmax, p0[r]); for (int r = 0; r < 16; ++r) pmax = fmaxf(pmax, p1[r]);
;   { auto rr = __builtin_amdgcn_permlane32_swap(__float_as_uint(pmax), __float_as_uint(pmax), false, false);
;     pmax = fmaxf(__uint_as_float(rr[0]), __uint_as_float(rr[1])); }
;   if (__builtin_expect(__all(pmax - m_reg <= THR / SCALE), 1)) { mn = m_reg; alpha = 1.f; }
;   else { mn = fmaxf(m_reg, pmax); alpha = __builtin_amdgcn_exp2f((m_reg - mn) * C); m_reg = mn; }
;   float mnC = -mn * C;
;   for (int r = 0; r < 16; ++r) p0[r] = fmaf(p0[r], C, mnC); for (int r = 0; r < 16; ++r) p1[r] = fmaf(p1[r], C, mnC);
;   for (int r = 0; r < 16; ++r) p0[r] = __builtin_amdgcn_exp2f(p0[r]);
; }
; __device__ __forceinline__ void finishSM(f32x16& p0, f32x16& p1, float alpha, float& l_reg, bf16x8& pa0, bf16x8& pa1, bf16x8& pa2, bf16x8& pa3) {
;   for (int r = 0; r < 16; ++r) p1[r] = __builtin_amdgcn_exp2f(p1[r]);
;   float ps = 0; for (int r = 0; r < 16; ++r) ps += p0[r]; for (int r = 0; r < 16; ++r) ps += p1[r];
;   { auto rr = __builtin_amdgcn_permlane32_swap(__float_as_uint(ps), __float_as_uint(ps), false, false);
;     ps = __uint_as_float(rr[0]) + __uint_as_float(rr[1]); }
;   l_reg = l_reg * alpha + ps;
;     ...
;   PK4(p0, 0, pa0); PK4(p0, 8, pa1); PK4(p1, 0, pa2); PK4(p1, 8, pa3);
; __device__ __forceinline__ void attn_unit(const bf16_t* __restrict__ Qb, const bf16_t* __restrict__ KV, const bf16_t* __restrict__ KP, bf16_t* __restrict__ Ob, ...
;     ...
;     __syncthreads(); SWAIT(); SWRITE(0);
;     RESC(alB); __syncthreads();
;     SBAR(); qkt(pA0, pA1, KN_lds, KP_lds, qr, r32, hi);
;     finishSM(pB0, pB1, alB, l_reg, pa0, pa1, pa2, pa3); SBAR();
;     SLOAD(j + 2); SBAR();
;     pv_d0(o, vb0 + SHM_V, pa0, pa1, pa2, pa3); partialSM(pA0, pA1, m_reg, mnA, alA);
;     __syncthreads(); SWAIT(); SWRITE(1);
	s_waitcnt vmcnt(0)
	ds_write_b128 v246, v[232:235]
	ds_write_b128 v247, v[236:239]
	ds_write_b128 v248, v[240:243]
	ds_write_b128 v244, v[224:227]
	ds_write_b128 v245, v[228:231]
	v_xor_b32_e32 v244, 0x4000, v244
	v_xor_b32_e32 v245, 0x4000, v245
	v_xor_b32_e32 v246, 0x4000, v246
	v_xor_b32_e32 v247, 0x4000, v247
	v_xor_b32_e32 v248, 0x2000, v248
	s_add_i32 s36, s35, 2
	s_min_u32 s36, s36, 67
	s_lshl_b32 s44, s36, 6
	s_add_i32 s45, s31, s44
	s_add_i32 s46, s24, s44
	s_add_i32 s46, s46, 0xffffff00
	s_cmp_lt_u32 s36, 4
	s_cselect_b32 s36, s45, s46
	s_add_i32 s37, s35, 1
	s_min_u32 s37, s37, 67
	s_lshl_b32 s44, s37, 6
	s_add_i32 s45, s31, s44
	s_add_i32 s46, s24, s44
	s_add_i32 s46, s46, 0xffffff00
	s_cmp_lt_u32 s37, 4
	s_cselect_b32 s37, s45, s46
	s_add_i32 s35, s35, 1
	s_lshl_b32 s44, s36, 12
	s_add_u32 s50, s47, s44
	s_addc_u32 s51, s63, 0
	s_add_u32 s52, s50, 0x20000
	s_addc_u32 s53, s51, 0
	s_lshl_b32 s44, s37, 12
	s_add_u32 s54, s47, s44
	s_addc_u32 s55, s63, 0
	s_add_u32 s56, s54, 0x20000
	s_addc_u32 s57, s55, 0
	s_lshl_b32 s44, s36, 10
	s_add_u32 s58, s60, s44
	s_addc_u32 s59, s61, 0
	global_load_dwordx4 v[232:235], v180, s[50:51]
	global_load_dwordx4 v[236:239], v180, s[52:53]
	global_load_dwordx4 v[224:227], v180, s[54:55] offset:256
	global_load_dwordx4 v[228:231], v180, s[56:57] offset:256
	global_load_dwordx4 v[240:243], v181, s[58:59]
	s_cmp_lg_u32 s62, 0
	s_cbranch_scc1 .Lpp_safe_b
	v_max3_f32 v250, v80, v81, v82
	v_max3_f32 v250, v250, v83, v84
	v_max3_f32 v250, v250, v85, v86
	v_max3_f32 v250, v250, v87, v88
	v_max3_f32 v250, v250, v89, v90
	v_max3_f32 v250, v250, v91, v92
	v_max3_f32 v250, v250, v93, v94
	v_max3_f32 v250, v250, v95, v64
	v_max3_f32 v250, v250, v65, v66
	v_max3_f32 v250, v250, v67, v68
	v_max3_f32 v250, v250, v69, v70
	v_max3_f32 v250, v250, v71, v72
	v_max3_f32 v250, v250, v73, v74
	v_max3_f32 v250, v250, v75, v76
	v_max3_f32 v250, v250, v77, v78
	v_max3_f32 v250, v250, v79, v79
	v_cmp_lt_f32_e64 vcc, s64, |v250|
	s_nop 4
	s_cbranch_vccnz .Lpp_sw_b
	v_exp_f32_e32 v80, v80
	v_exp_f32_e32 v81, v81
	v_exp_f32_e32 v82, v82
	v_exp_f32_e32 v83, v83
	v_exp_f32_e32 v84, v84
	v_exp_f32_e32 v85, v85
	v_exp_f32_e32 v86, v86
	v_exp_f32_e32 v87, v87
	v_exp_f32_e32 v88, v88
	v_exp_f32_e32 v89, v89
	v_exp_f32_e32 v90, v90
	v_exp_f32_e32 v91, v91
	v_exp_f32_e32 v92, v92
	v_exp_f32_e32 v93, v93
	v_exp_f32_e32 v94, v94
	v_exp_f32_e32 v95, v95
	v_exp_f32_e32 v64, v64
	v_exp_f32_e32 v65, v65
	v_exp_f32_e32 v66, v66
	v_exp_f32_e32 v67, v67
	v_exp_f32_e32 v68, v68
	v_exp_f32_e32 v69, v69
	v_exp_f32_e32 v70, v70
	v_exp_f32_e32 v71, v71
	v_exp_f32_e32 v72, v72
	v_exp_f32_e32 v73, v73
	v_exp_f32_e32 v74, v74
	v_exp_f32_e32 v75, v75
	v_exp_f32_e32 v76, v76
	v_exp_f32_e32 v77, v77
	v_exp_f32_e32 v78, v78
	v_exp_f32_e32 v79, v79
	s_nop 0
	v_add_f32_e32 v249, v80, v81
	v_add_f32_e32 v249, v82, v249
	v_add_f32_e32 v249, v83, v249
	v_add_f32_e32 v249, v84, v249
	v_add_f32_e32 v249, v85, v249
	v_add_f32_e32 v249, v86, v249
	v_add_f32_e32 v249, v87, v249
	v_add_f32_e32 v249, v88, v249
	v_add_f32_e32 v249, v89, v249
	v_add_f32_e32 v249, v90, v249
	v_add_f32_e32 v249, v91, v249
	v_add_f32_e32 v249, v92, v249
	v_add_f32_e32 v249, v93, v249
	v_add_f32_e32 v249, v94, v249
	v_add_f32_e32 v249, v95, v249
	v_add_f32_e32 v249, v64, v249
	v_add_f32_e32 v249, v65, v249
	v_add_f32_e32 v249, v66, v249
	v_add_f32_e32 v249, v67, v249
	v_add_f32_e32 v249, v68, v249
	v_add_f32_e32 v249, v69, v249
	v_add_f32_e32 v249, v70, v249
	v_add_f32_e32 v249, v71, v249
	v_add_f32_e32 v249, v72, v249
	v_add_f32_e32 v249, v73, v249
	v_add_f32_e32 v249, v74, v249
	v_add_f32_e32 v249, v75, v249
	v_add_f32_e32 v249, v76, v249
	v_add_f32_e32 v249, v77, v249
	v_add_f32_e32 v249, v78, v249
	v_add_f32_e32 v249, v79, v249
	v_add_f32_e32 v176, v176, v249
	v_cvt_pk_bf16_f32 v144, v80, v81
	v_cvt_pk_bf16_f32 v145, v82, v83
	v_cvt_pk_bf16_f32 v146, v84, v85
	v_cvt_pk_bf16_f32 v147, v86, v87
	v_cvt_pk_bf16_f32 v148, v88, v89
	v_cvt_pk_bf16_f32 v149, v90, v91
	v_cvt_pk_bf16_f32 v150, v92, v93
	v_cvt_pk_bf16_f32 v151, v94, v95
	v_cvt_pk_bf16_f32 v152, v64, v65
	v_cvt_pk_bf16_f32 v153, v66, v67
	v_cvt_pk_bf16_f32 v154, v68, v69
	v_cvt_pk_bf16_f32 v155, v70, v71
	v_cvt_pk_bf16_f32 v156, v72, v73
	v_cvt_pk_bf16_f32 v157, v74, v75
	v_cvt_pk_bf16_f32 v158, v76, v77
	v_cvt_pk_bf16_f32 v159, v78, v79
	s_nop 1
	v_permlane32_swap_b32_e32 v144, v146
	v_permlane32_swap_b32_e32 v145, v147
	v_permlane32_swap_b32_e32 v148, v150
	v_permlane32_swap_b32_e32 v149, v151
	v_permlane32_swap_b32_e32 v152, v154
	v_permlane32_swap_b32_e32 v153, v155
	v_permlane32_swap_b32_e32 v156, v158
	v_permlane32_swap_b32_e32 v157, v159
	s_branch .Lpp_send_b

; __device__ __forceinline__ void qkt(f32x16& p0, f32x16& p1, const char* Kn, const char* Kp, const bf16x8* qr, int r32, int hi) {
;   p0 = f32x16{}; p1 = f32x16{};
; #pragma unroll
;   for (int d0 = 0; d0 < 8; ++d0) { int cb = (d0 * 16 + hi * 8) * 2;
;     bf16x8 b0 = *reinterpret_cast<const bf16x8*>(Kn + KSWZ(r32, cb));
;     bf16x8 b1 = *reinterpret_cast<const bf16x8*>(Kn + KSWZ(32 + r32, cb));
;     p0 = __builtin_amdgcn_mfma_f32_32x32x16_bf16(b0, qr[d0], p0, 0, 0, 0);
;     p1 = __builtin_amdgcn_mfma_f32_32x32x16_bf16(b1, qr[d0], p1, 0, 0, 0); }
; #pragma unroll
;   for (int d1 = 0; d1 < 4; ++d1) { int cb = (d1 * 16 + hi * 8) * 2;
;     bf16x8 b0 = *reinterpret_cast<const bf16x8*>(Kp + KPSWZ(r32, cb));
;     bf16x8 b1 = *reinterpret_cast<const bf16x8*>(Kp + KPSWZ(32 + r32, cb));
;     p0 = __builtin_amdgcn_mfma_f32_32x32x16_bf16(b0, qr[8 + d1], p0, 0, 0, 0);
;     p1 = __builtin_amdgcn_mfma_f32_32x32x16_bf16(b1, qr[8 + d1], p1, 0, 0, 0); }
; }
; __device__ __forceinline__ int v_st(int k, int c) { const int kk = (k & ~0xC) | ((k & 4) << 1) | ((k & 8) >> 1); return ((kk >> 3) * 4 + (c >> 5)) * 512 + ((kk & 7) * 32 + (c & 31)) * 2; }
; __device__ __forceinline__ int v_rd_base(int lane) { return ((lane & 3) << 3) | (((lane >> 2) & 3) << 6) | (((lane >> 4) & 1) << 5) | (((lane >> 5) & 1) << 8); }
; template <int OFF> __device__ __forceinline__ s16x4 tr_read(int vb) {
;   s16x4 r; asm volatile("ds_read_b64_tr_b16 %0, %1 offset:%2" : "=&v"(r) : "v"(vb), "i"(OFF) : "memory"); return r;
; }
; template <int D0> __device__ __forceinline__ void pv_one(f32x16& od, int vb, bf16x8 pa0, bf16x8 pa1, bf16x8 pa2, bf16x8 pa3) {
;   const s16x4 l0 = tr_read<v_rd_off(D0, 0, 0)>(vb), h0 = tr_read<v_rd_off(D0, 0, 1)>(vb), l1 = tr_read<v_rd_off(D0, 1, 0)>(vb), h1 = tr_read<v_rd_off(D0, 1, 1)>(vb);
;   const s16x4 l2 = tr_read<v_rd_off(D0, 2, 0)>(vb), h2 = tr_read<v_rd_off(D0, 2, 1)>(vb), l3 = tr_read<v_rd_off(D0, 3, 0)>(vb), h3 = tr_read<v_rd_off(D0, 3, 1)>(vb);
;   asm volatile("s_waitcnt lgkmcnt(0)" ::: "memory"); SBAR();
;     ...
;   od = __builtin_amdgcn_mfma_f32_32x32x16_bf16(pa0, PK(l0, h0), od, 0, 0, 0);
;   od = __builtin_amdgcn_mfma_f32_32x32x16_bf16(pa1, PK(l1, h1), od, 0, 0, 0);
;   od = __builtin_amdgcn_mfma_f32_32x32x16_bf16(pa2, PK(l2, h2), od, 0, 0, 0);
;   od = __builtin_amdgcn_mfma_f32_32x32x16_bf16(pa3, PK(l3, h3), od, 0, 0, 0);
;     ...
; }
.Lpp_send_b:
	s_waitcnt lgkmcnt(0)
	s_barrier
	s_add_i32 s11, s11, 1
	s_cmp_eq_u32 s11, 68
	s_cbranch_scc1 .Lpp_last
	ds_read_b128 v[192:195], v160
	ds_read_b128 v[196:199], v160 offset:8192
	ds_read_b128 v[200:203], v161
	ds_read_b128 v[204:207], v161 offset:8192
	ds_read_b128 v[208:211], v162
	ds_read_b128 v[212:215], v162 offset:8192
	ds_read_b128 v[216:219], v163
	ds_read_b128 v[220:223], v163 offset:8192
	s_waitcnt lgkmcnt(6)
	v_mfma_f32_32x32x16_bf16 v[80:95], v[192:195], v[136:139], 0
	v_mfma_f32_32x32x16_bf16 v[64:79], v[196:199], v[136:139], 0
	ds_read_b128 v[192:195], v164
	ds_read_b128 v[196:199], v164 offset:8192
	s_waitcnt lgkmcnt(6)
	v_mfma_f32_32x32x16_bf16 v[80:95], v[200:203], v[132:135], v[80:95]
	v_mfma_f32_32x32x16_bf16 v[64:79], v[204:207], v[132:135], v[64:79]
	ds_read_b128 v[200:203], v165
	ds_read_b128 v[204:207], v165 offset:8192
	s_waitcnt lgkmcnt(6)
	v_mfma_f32_32x32x16_bf16 v[80:95], v[208:211], v[128:131], v[80:95]
	v_mfma_f32_32x32x16_bf16 v[64:79], v[212:215], v[128:131], v[64:79]
	ds_read_b128 v[208:211], v166
	ds_read_b128 v[212:215], v166 offset:8192
	s_waitcnt lgkmcnt(6)
	v_mfma_f32_32x32x16_bf16 v[80:95], v[216:219], v[124:127], v[80:95]
	v_mfma_f32_32x32x16_bf16 v[64:79], v[220:223], v[124:127], v[64:79]
	ds_read_b128 v[216:219], v167
	ds_read_b128 v[220:223], v167 offset:8192
	s_waitcnt lgkmcnt(6)
	v_mfma_f32_32x32x16_bf16 v[80:95], v[192:195], v[120:123], v[80:95]
	v_mfma_f32_32x32x16_bf16 v[64:79], v[196:199], v[120:123], v[64:79]
	ds_read_b128 v[192:195], v168
	ds_read_b128 v[196:199], v168 offset:4096
	s_waitcnt lgkmcnt(6)
	v_mfma_f32_32x32x16_bf16 v[80:95], v[200:203], v[140:143], v[80:95]
	v_mfma_f32_32x32x16_bf16 v[64:79], v[204:207], v[140:143], v[64:79]
	ds_read_b128 v[200:203], v169
	ds_read_b128 v[204:207], v169 offset:4096
	s_waitcnt lgkmcnt(6)
	v_mfma_f32_32x32x16_bf16 v[80:95], v[208:211], v[116:119], v[80:95]
	v_mfma_f32_32x32x16_bf16 v[64:79], v[212:215], v[116:119], v[64:79]
	ds_read_b128 v[208:211], v170
	ds_read_b128 v[212:215], v170 offset:4096
	s_waitcnt lgkmcnt(6)
	v_mfma_f32_32x32x16_bf16 v[80:95], v[216:219], v[112:115], v[80:95]
	v_mfma_f32_32x32x16_bf16 v[64:79], v[220:223], v[112:115], v[64:79]
	ds_read_b128 v[216:219], v171
	ds_read_b128 v[220:223], v171 offset:4096
	s_waitcnt lgkmcnt(6)
	v_mfma_f32_32x32x16_bf16 v[80:95], v[192:195], v[108:111], v[80:95]
	v_mfma_f32_32x32x16_bf16 v[64:79], v[196:199], v[108:111], v[64:79]
	ds_read_b64_tr_b16 v[192:193], v174 offset:16384
	ds_read_b64_tr_b16 v[194:195], v174 offset:18432
	ds_read_b64_tr_b16 v[196:197], v174 offset:20480
	ds_read_b64_tr_b16 v[198:199], v174 offset:22528
	s_waitcnt lgkmcnt(8)
	v_mfma_f32_32x32x16_bf16 v[80:95], v[200:203], v[104:107], v[80:95]
	v_mfma_f32_32x32x16_bf16 v[64:79], v[204:207], v[104:107], v[64:79]
	ds_read_b64_tr_b16 v[200:201], v174 offset:24576
	ds_read_b64_tr_b16 v[202:203], v174 offset:26624
	ds_read_b64_tr_b16 v[204:205], v174 offset:28672
	ds_read_b64_tr_b16 v[206:207], v174 offset:30720
	s_waitcnt lgkmcnt(10)
	v_mfma_f32_32x32x16_bf16 v[80:95], v[208:211], v[100:103], v[80:95]
	v_mfma_f32_32x32x16_bf16 v[64:79], v[212:215], v[100:103], v[64:79]
	ds_read_b64_tr_b16 v[208:209], v174 offset:16896
	ds_read_b64_tr_b16 v[210:211], v174 offset:18944
	ds_read_b64_tr_b16 v[212:213], v174 offset:20992
	ds_read_b64_tr_b16 v[214:215], v174 offset:23040
	s_waitcnt lgkmcnt(12)
	v_mfma_f32_32x32x16_bf16 v[80:95], v[216:219], v[96:99], v[80:95]
	v_mfma_f32_32x32x16_bf16 v[64:79], v[220:223], v[96:99], v[64:79]
	ds_read_b64_tr_b16 v[216:217], v174 offset:25088
	ds_read_b64_tr_b16 v[218:219], v174 offset:27136
	ds_read_b64_tr_b16 v[220:221], v174 offset:29184
	ds_read_b64_tr_b16 v[222:223], v174 offset:31232
	s_waitcnt lgkmcnt(12)
	v_mfma_f32_32x32x16_bf16 v[0:15], v[144:147], v[192:195], v[0:15]
	ds_read_b64_tr_b16 v[192:193], v174 offset:17408
	ds_read_b64_tr_b16 v[194:195], v174 offset:19456
	v_mfma_f32_32x32x16_bf16 v[0:15], v[148:151], v[196:199], v[0:15]
	ds_read_b64_tr_b16 v[196:197], v174 offset:21504
	ds_read_b64_tr_b16 v[198:199], v174 offset:23552
	s_waitcnt lgkmcnt(12)
	v_mfma_f32_32x32x16_bf16 v[0:15], v[152:155], v[200:203], v[0:15]
	ds_read_b64_tr_b16 v[200:201], v174 offset:25600
	ds_read_b64_tr_b16 v[202:203], v174 offset:27648
	v_mfma_f32_32x32x16_bf16 v[0:15], v[156:159], v[204:207], v[0:15]
	ds_read_b64_tr_b16 v[204:205], v174 offset:29696
	ds_read_b64_tr_b16 v[206:207], v174 offset:31744
	s_waitcnt lgkmcnt(12)
	v_mfma_f32_32x32x16_bf16 v[48:63], v[144:147], v[208:211], v[48:63]
	ds_read_b64_tr_b16 v[208:209], v174 offset:17920
	ds_read_b64_tr_b16 v[210:211], v174 offset:19968
	v_mfma_f32_32x32x16_bf16 v[48:63], v[148:151], v[212:215], v[48:63]
	ds_read_b64_tr_b16 v[212:213], v174 offset:22016
	ds_read_b64_tr_b16 v[214:215], v174 offset:24064
	s_waitcnt lgkmcnt(12)
	v_mfma_f32_32x32x16_bf16 v[48:63], v[152:155], v[216:219], v[48:63]
	ds_read_b64_tr_b16 v[216:217], v174 offset:26112
	ds_read_b64_tr_b16 v[218:219], v174 offset:28160
	v_mfma_f32_32x32x16_bf16 v[48:63], v[156:159], v[220:223], v[48:63]
	ds_read_b64_tr_b16 v[220:221], v174 offset:30208
	ds_read_b64_tr_b16 v[222:223], v174 offset:32256
	s_waitcnt lgkmcnt(12)
	v_mfma_f32_32x32x16_bf16 v[32:47], v[144:147], v[192:195], v[32:47]
	v_mfma_f32_32x32x16_bf16 v[32:47], v[148:151], v[196:199], v[32:47]
	s_waitcnt lgkmcnt(8)
	v_mfma_f32_32x32x16_bf16 v[32:47], v[152:155], v[200:203], v[32:47]
	v_mfma_f32_32x32x16_bf16 v[32:47], v[156:159], v[204:207], v[32:47]
	s_waitcnt lgkmcnt(4)
	v_mfma_f32_32x32x16_bf16 v[16:31], v[144:147], v[208:211], v[16:31]
	v_mfma_f32_32x32x16_bf16 v[16:31], v[148:151], v[212:215], v[16:31]
	s_waitcnt lgkmcnt(0)
	v_mfma_f32_32x32x16_bf16 v[16:31], v[152:155], v[216:219], v[16:31]
	v_mfma_f32_32x32x16_bf16 v[16:31], v[156:159], v[220:223], v[16:31]
	s_barrier
	s_branch .Lpp_loop
